# v083 + P0 row-RMS reductions: 6-step ds_bpermute butterflies replaced by DPP adds (quad_perm / row_half_mirror / row_mirror) + permlane16/32 swaps, bitwise-identical sums
# speedup vs baseline: 1.0022x; 1.0020x over previous
.LBB0_24:
	v_mul_f32_e32 v51, v51, v51
	v_mul_f32_e32 v43, v43, v43
	v_fmac_f32_e32 v51, v50, v50
	v_mul_f32_e32 v50, v53, v53
	v_fmac_f32_e32 v43, v42, v42
	v_mul_f32_e32 v42, v45, v45
	v_mul_f32_e32 v39, v39, v39
	v_fmac_f32_e32 v50, v52, v52
	v_fmac_f32_e32 v42, v44, v44
	v_fmac_f32_e32 v39, v38, v38
	v_mul_f32_e32 v38, v41, v41
	v_mul_f32_e32 v31, v31, v31
	v_add_f32_e32 v50, v51, v50
	s_waitcnt vmcnt(11)
	v_mul_f32_e32 v51, v63, v63
	v_mul_f32_e32 v52, v65, v65
	v_add_f32_e32 v42, v43, v42
	s_waitcnt vmcnt(10)
	v_mul_f32_e32 v43, v59, v59
	v_mul_f32_e32 v44, v61, v61
	v_fmac_f32_e32 v38, v40, v40
	v_fmac_f32_e32 v31, v30, v30
	v_mul_f32_e32 v30, v33, v33
	v_mul_f32_e32 v23, v23, v23
	v_fmac_f32_e32 v51, v62, v62
	v_fmac_f32_e32 v52, v64, v64
	v_fmac_f32_e32 v43, v58, v58
	v_fmac_f32_e32 v44, v60, v60
	v_add_f32_e32 v38, v39, v38
	s_waitcnt vmcnt(9)
	v_mul_f32_e32 v39, v55, v55
	v_mul_f32_e32 v40, v57, v57
	v_fmac_f32_e32 v30, v32, v32
	v_fmac_f32_e32 v23, v22, v22
	v_mul_f32_e32 v22, v25, v25
	v_mul_f32_e32 v19, v19, v19
	v_add_f32_e32 v51, v51, v52
	v_add_f32_e32 v43, v43, v44
	v_fmac_f32_e32 v39, v54, v54
	v_fmac_f32_e32 v40, v56, v56
	v_add_f32_e32 v30, v31, v30
	s_waitcnt vmcnt(8)
	v_mul_f32_e32 v31, v47, v47
	v_mul_f32_e32 v32, v49, v49
	v_fmac_f32_e32 v22, v24, v24
	v_fmac_f32_e32 v19, v18, v18
	v_mul_f32_e32 v18, v21, v21
	v_mul_f32_e32 v11, v11, v11
	v_add_f32_e32 v42, v50, v42
	v_add_f32_e32 v43, v51, v43
	v_add_f32_e32 v39, v39, v40
	v_fmac_f32_e32 v31, v46, v46
	v_fmac_f32_e32 v32, v48, v48
	v_add_f32_e32 v22, v23, v22
	v_mul_f32_e32 v23, v35, v35
	v_mul_f32_e32 v24, v37, v37
	v_fmac_f32_e32 v18, v20, v20
	v_fmac_f32_e32 v11, v10, v10
	v_mul_f32_e32 v10, v13, v13
	v_mul_f32_e32 v3, v3, v3
	v_add_f32_e32 v38, v42, v38
	v_add_f32_e32 v39, v43, v39
	v_add_f32_e32 v31, v31, v32
	v_fmac_f32_e32 v23, v34, v34
	v_fmac_f32_e32 v24, v36, v36
	v_add_f32_e32 v18, v19, v18
	v_mul_f32_e32 v19, v27, v27
	v_mul_f32_e32 v20, v29, v29
	v_fmac_f32_e32 v10, v12, v12
	v_fmac_f32_e32 v3, v2, v2
	v_mul_f32_e32 v2, v5, v5
	v_add_f32_e32 v30, v38, v30
	v_add_f32_e32 v31, v39, v31
	v_add_f32_e32 v23, v23, v24
	v_fmac_f32_e32 v19, v26, v26
	v_fmac_f32_e32 v20, v28, v28
	v_add_f32_e32 v10, v11, v10
	v_mul_f32_e32 v11, v15, v15
	v_mul_f32_e32 v12, v17, v17
	v_fmac_f32_e32 v2, v4, v4
	v_add_f32_e32 v22, v30, v22
	v_add_f32_e32 v23, v31, v23
	v_add_f32_e32 v19, v19, v20
	v_fmac_f32_e32 v11, v14, v14
	v_fmac_f32_e32 v12, v16, v16
	v_add_f32_e32 v2, v3, v2
	v_mul_f32_e32 v3, v7, v7
	v_mul_f32_e32 v4, v9, v9
	v_add_f32_e32 v18, v22, v18
	v_add_f32_e32 v19, v23, v19
	v_add_f32_e32 v11, v11, v12
	v_fmac_f32_e32 v3, v6, v6
	v_fmac_f32_e32 v4, v8, v8
	v_add_f32_e32 v10, v18, v10
	v_add_f32_e32 v11, v19, v11
	v_add_f32_e32 v3, v3, v4
	v_add_f32_e32 v2, v10, v2
	v_add_f32_e32 v3, v11, v3
	s_nop 0
	v_add_f32_dpp v2, v2, v2 quad_perm:[1,0,3,2] row_mask:0xf bank_mask:0xf
	v_add_f32_dpp v3, v3, v3 quad_perm:[1,0,3,2] row_mask:0xf bank_mask:0xf
	s_nop 0
	v_add_f32_dpp v2, v2, v2 quad_perm:[2,3,0,1] row_mask:0xf bank_mask:0xf
	v_add_f32_dpp v3, v3, v3 quad_perm:[2,3,0,1] row_mask:0xf bank_mask:0xf
	s_nop 0
	v_add_f32_dpp v2, v2, v2 row_half_mirror row_mask:0xf bank_mask:0xf
	v_add_f32_dpp v3, v3, v3 row_half_mirror row_mask:0xf bank_mask:0xf
	s_nop 0
	v_add_f32_dpp v2, v2, v2 row_mirror row_mask:0xf bank_mask:0xf
	v_add_f32_dpp v3, v3, v3 row_mirror row_mask:0xf bank_mask:0xf
	v_mov_b32_e32 v4, v2
	v_mov_b32_e32 v6, v3
	s_nop 1
	v_permlane16_swap_b32_e32 v2, v4
	v_permlane16_swap_b32_e32 v3, v6
	v_add_f32_e32 v4, v2, v4
	v_add_f32_e32 v2, v3, v6
	v_mov_b32_e32 v5, v4
	v_mov_b32_e32 v3, v2
	s_nop 1
	v_permlane32_swap_b32_e32 v4, v5
	v_permlane32_swap_b32_e32 v2, v3
	s_and_saveexec_b64 s[40:41], s[6:7]
	s_cbranch_execz .LBB0_7
	s_waitcnt lgkmcnt(1)
	v_add_f32_e32 v4, v4, v5
	v_fmamk_f32 v4, v4, 0x3a000000, v82
	v_mul_f32_e32 v5, 0x4f800000, v4
	v_cmp_gt_f32_e32 vcc, s33, v4
	s_nop 1
	v_cndmask_b32_e32 v4, v4, v5, vcc
	v_sqrt_f32_e32 v5, v4
	s_nop 0
	v_add_u32_e32 v6, -1, v5
	v_fma_f32 v8, -v6, v5, v4
	v_add_u32_e32 v7, 1, v5
	v_cmp_ge_f32_e64 s[8:9], 0, v8
	s_nop 1
	v_cndmask_b32_e64 v6, v5, v6, s[8:9]
	v_fma_f32 v5, -v7, v5, v4
	v_cmp_lt_f32_e64 s[8:9], 0, v5
	s_nop 1
	v_cndmask_b32_e64 v5, v6, v7, s[8:9]
	v_mul_f32_e32 v6, 0x37800000, v5
	v_cndmask_b32_e32 v5, v5, v6, vcc
	v_cmp_class_f32_e32 vcc, v4, v83
	s_nop 1
	v_cndmask_b32_e32 v4, v5, v4, vcc
	v_div_scale_f32 v5, s[8:9], v4, v4, 1.0
	v_rcp_f32_e32 v6, v5
	s_lshl_b64 s[8:9], s[38:39], 2
	s_add_u32 s8, s68, s8
	s_addc_u32 s9, s69, s9
	v_fma_f32 v7, -v5, v6, 1.0
	v_fmac_f32_e32 v6, v7, v6
	v_div_scale_f32 v7, vcc, 1.0, v4, 1.0
	v_mul_f32_e32 v8, v7, v6
	v_fma_f32 v9, -v5, v8, v7
	v_fmac_f32_e32 v8, v9, v6
	v_fma_f32 v5, -v5, v8, v7
	v_div_fmas_f32 v5, v5, v6, v8
	v_div_fixup_f32 v4, v5, v4, 1.0
	s_and_b64 vcc, exec, s[4:5]
	global_store_dword v71, v4, s[8:9]
	s_cbranch_vccnz .LBB0_7
	s_waitcnt lgkmcnt(0)
	v_add_f32_e32 v2, v2, v3
	v_fmamk_f32 v2, v2, 0x3a000000, v82
	v_mul_f32_e32 v3, 0x4f800000, v2
	v_cmp_gt_f32_e32 vcc, s33, v2
	s_nop 1
	v_cndmask_b32_e32 v2, v2, v3, vcc
	v_sqrt_f32_e32 v3, v2
	s_nop 0
	v_add_u32_e32 v4, -1, v3
	v_fma_f32 v6, -v4, v3, v2
	v_add_u32_e32 v5, 1, v3
	v_cmp_ge_f32_e64 s[4:5], 0, v6
	s_nop 1
	v_cndmask_b32_e64 v4, v3, v4, s[4:5]
	v_fma_f32 v3, -v5, v3, v2
	v_cmp_lt_f32_e64 s[4:5], 0, v3
	s_nop 1
	v_cndmask_b32_e64 v3, v4, v5, s[4:5]
	v_mul_f32_e32 v4, 0x37800000, v3
	v_cndmask_b32_e32 v3, v3, v4, vcc
	v_cmp_class_f32_e32 vcc, v2, v83
	s_nop 1
	v_cndmask_b32_e32 v2, v3, v2, vcc
	v_div_scale_f32 v3, s[4:5], v2, v2, 1.0
	v_rcp_f32_e32 v4, v3
	s_add_u32 s4, s8, s34
	s_addc_u32 s5, s9, s35
	v_fma_f32 v5, -v3, v4, 1.0
	v_fmac_f32_e32 v4, v5, v4
	v_div_scale_f32 v5, vcc, 1.0, v2, 1.0
	v_mul_f32_e32 v6, v5, v4
	v_fma_f32 v7, -v3, v6, v5
	v_fmac_f32_e32 v6, v7, v4
	v_fma_f32 v3, -v3, v6, v5
	v_div_fmas_f32 v3, v3, v4, v6
	v_div_fixup_f32 v2, v3, v2, 1.0
	global_store_dword v71, v2, s[4:5]
	s_branch .LBB0_7

.LBB0_29:
	v_add_co_u32_e32 v44, vcc, 0xfffff000, v20
	global_load_dwordx4 v[6:9], v[20:21], off offset:-3072
	global_load_dwordx4 v[32:35], v[20:21], off offset:-2048
	global_load_dwordx4 v[2:5], v[20:21], off
	v_addc_co_u32_e32 v45, vcc, -1, v21, vcc
	global_load_dwordx4 v[36:39], v[44:45], off offset:-3072
	global_load_dwordx4 v[40:43], v[44:45], off offset:-2048
	s_nop 0
	global_load_dwordx4 v[44:47], v[44:45], off offset:-1024
	s_nop 0
	global_load_dwordx4 v[48:51], v[20:21], off offset:-4096
	global_load_dwordx4 v[52:55], v[20:21], off offset:-1024
	global_load_dwordx4 v[56:59], v[10:11], off
	s_add_i32 s9, s9, s30
	s_cmpk_gt_i32 s9, 0x3ff
	v_lshl_add_u64 v[20:21], v[20:21], 0, s[4:5]
	s_waitcnt vmcnt(5)
	v_mov_b32_e32 v76, v37
	v_pk_mul_f32 v[60:61], v[34:35], v[34:35]
	v_pk_mul_f32 v[62:63], v[32:33], v[32:33]
	v_mul_f32_e32 v87, v4, v4
	s_waitcnt vmcnt(1)
	v_mul_f32_e32 v64, v53, v53
	v_mul_f32_e32 v72, v55, v55
	v_mul_f32_e32 v92, v5, v5
	v_pk_mov_b32 v[74:75], v[62:63], v[60:61] op_sel:[1,0]
	v_mov_b32_e32 v63, v61
	v_pk_fma_f32 v[60:61], v[52:53], v[52:53], v[64:65] op_sel_hi:[1,1,0]
	v_pk_fma_f32 v[64:65], v[54:55], v[54:55], v[72:73] op_sel_hi:[1,1,0]
	v_mov_b32_e32 v77, v41
	v_mov_b32_e32 v80, v39
	v_mov_b32_e32 v81, v43
	v_mov_b32_e32 v72, v36
	v_mov_b32_e32 v73, v40
	v_mov_b32_e32 v78, v38
	v_mov_b32_e32 v79, v42
	v_pk_mul_f32 v[82:83], v[46:47], v[46:47]
	v_pk_mul_f32 v[84:85], v[44:45], v[44:45]
	v_pk_add_f32 v[62:63], v[74:75], v[62:63]
	v_mov_b32_e32 v61, v87
	v_mov_b32_e32 v65, v92
	v_pk_mul_f32 v[74:75], v[76:77], v[76:77]
	v_pk_mul_f32 v[76:77], v[80:81], v[80:81]
	v_pk_mov_b32 v[80:81], v[84:85], v[82:83] op_sel:[1,0]
	v_mov_b32_e32 v85, v83
	v_pk_add_f32 v[60:61], v[60:61], v[64:65]
	v_pk_fma_f32 v[64:65], v[72:73], v[72:73], v[74:75]
	v_pk_fma_f32 v[72:73], v[78:79], v[78:79], v[76:77]
	v_mul_f32_e32 v89, v9, v9
	v_mul_f32_e32 v86, v49, v49
	v_mul_f32_e32 v88, v51, v51
	v_pk_add_f32 v[74:75], v[80:81], v[84:85]
	v_pk_add_f32 v[64:65], v[64:65], v[72:73]
	v_mul_f32_e32 v67, v6, v6
	v_mul_f32_e32 v69, v7, v7
	v_mul_f32_e32 v71, v8, v8
	v_pk_fma_f32 v[82:83], v[48:49], v[48:49], v[86:87] op_sel_hi:[1,1,0]
	v_pk_fma_f32 v[86:87], v[50:51], v[50:51], v[88:89] op_sel_hi:[1,1,0]
	v_pk_add_f32 v[72:73], v[74:75], v[74:75] op_sel:[0,1] op_sel_hi:[1,0]
	v_pk_add_f32 v[64:65], v[64:65], v[64:65] op_sel:[0,1] op_sel_hi:[1,0]
	v_mov_b32_e32 v83, v71
	v_mov_b32_e32 v87, v89
	v_mov_b32_e32 v73, v69
	v_mov_b32_e32 v65, v67
	v_pk_add_f32 v[74:75], v[82:83], v[86:87]
	v_pk_add_f32 v[64:65], v[64:65], v[72:73]
	v_mul_f32_e32 v90, v2, v2
	v_pk_add_f32 v[64:65], v[64:65], v[74:75]
	v_mul_f32_e32 v91, v3, v3
	v_pk_add_f32 v[62:63], v[62:63], v[62:63] op_sel:[0,1] op_sel_hi:[1,0]
	v_pk_add_f32 v[64:65], v[64:65], v[64:65] op_sel:[0,1] op_sel_hi:[1,0]
	v_mov_b32_e32 v63, v91
	v_mov_b32_e32 v65, v90
	v_pk_add_f32 v[62:63], v[64:65], v[62:63]
	s_nop 0
	v_pk_add_f32 v[60:61], v[62:63], v[60:61]
	s_nop 0
	v_add_f32_e32 v60, v60, v61
	s_nop 1
	v_add_f32_dpp v60, v60, v60 quad_perm:[1,0,3,2] row_mask:0xf bank_mask:0xf
	s_nop 1
	v_add_f32_dpp v60, v60, v60 quad_perm:[2,3,0,1] row_mask:0xf bank_mask:0xf
	s_nop 1
	v_add_f32_dpp v60, v60, v60 row_half_mirror row_mask:0xf bank_mask:0xf
	s_nop 1
	v_add_f32_dpp v60, v60, v60 row_mirror row_mask:0xf bank_mask:0xf
	v_mov_b32_e32 v61, v60
	s_nop 1
	v_permlane16_swap_b32_e32 v60, v61
	v_add_f32_e32 v60, v60, v61
	v_mov_b32_e32 v61, v60
	s_nop 1
	v_permlane32_swap_b32_e32 v60, v61
	v_add_f32_e32 v60, v60, v61
	v_fmamk_f32 v60, v60, 0x3a000000, v30
	v_mul_f32_e32 v61, 0x4f800000, v60
	v_cmp_gt_f32_e32 vcc, s8, v60
	s_nop 1
	v_cndmask_b32_e32 v60, v60, v61, vcc
	v_sqrt_f32_e32 v61, v60
	s_nop 0
	v_add_u32_e32 v62, -1, v61
	v_add_u32_e32 v63, 1, v61
	v_fma_f32 v64, -v62, v61, v60
	v_fma_f32 v65, -v63, v61, v60
	v_cmp_ge_f32_e64 s[0:1], 0, v64
	s_nop 1
	v_cndmask_b32_e64 v61, v61, v62, s[0:1]
	v_cmp_lt_f32_e64 s[0:1], 0, v65
	s_nop 1
	v_cndmask_b32_e64 v61, v61, v63, s[0:1]
	v_mul_f32_e32 v62, 0x37800000, v61
	v_cndmask_b32_e32 v61, v61, v62, vcc
	v_cmp_class_f32_e32 vcc, v60, v31
	s_nop 1
	v_cndmask_b32_e32 v60, v61, v60, vcc
	v_div_scale_f32 v61, s[0:1], v60, v60, 1.0
	v_rcp_f32_e32 v63, v61
	v_div_scale_f32 v62, vcc, 1.0, v60, 1.0
	v_fma_f32 v64, -v61, v63, 1.0
	v_fmac_f32_e32 v63, v64, v63
	v_mul_f32_e32 v64, v62, v63
	v_fma_f32 v65, -v61, v64, v62
	v_fmac_f32_e32 v64, v65, v63
	v_fma_f32 v61, -v61, v64, v62
	v_div_fmas_f32 v61, v61, v63, v64
	v_div_fixup_f32 v60, v61, v60, 1.0
	v_pk_mul_f32 v[36:37], v[36:37], v[60:61] op_sel_hi:[1,0]
	v_pk_mul_f32 v[38:39], v[38:39], v[60:61] op_sel_hi:[1,0]
	s_waitcnt vmcnt(0)
	v_pk_mul_f32 v[36:37], v[56:57], v[36:37]
	v_pk_mul_f32 v[38:39], v[58:59], v[38:39]
	v_cvt_pk_bf16_f32 v36, v36, v37
	v_cvt_pk_bf16_f32 v37, v38, v39
	global_store_dwordx2 v[22:23], v[36:37], off offset:-2048
	global_load_dwordx4 v[36:39], v[10:11], off offset:1024
	v_pk_mul_f32 v[40:41], v[40:41], v[60:61] op_sel_hi:[1,0]
	v_pk_mul_f32 v[42:43], v[42:43], v[60:61] op_sel_hi:[1,0]
	v_pk_mul_f32 v[6:7], v[6:7], v[60:61] op_sel_hi:[1,0]
	v_pk_mul_f32 v[8:9], v[8:9], v[60:61] op_sel_hi:[1,0]
	v_pk_mul_f32 v[32:33], v[32:33], v[60:61] op_sel_hi:[1,0]
	v_pk_mul_f32 v[34:35], v[34:35], v[60:61] op_sel_hi:[1,0]
	v_pk_mul_f32 v[2:3], v[2:3], v[60:61] op_sel_hi:[1,0]
	v_pk_mul_f32 v[4:5], v[4:5], v[60:61] op_sel_hi:[1,0]
	s_waitcnt vmcnt(0)
	v_pk_mul_f32 v[38:39], v[38:39], v[42:43]
	v_pk_mul_f32 v[36:37], v[36:37], v[40:41]
	v_pk_mul_f32 v[40:41], v[44:45], v[60:61] op_sel_hi:[1,0]
	v_cvt_pk_bf16_f32 v36, v36, v37
	v_cvt_pk_bf16_f32 v37, v38, v39
	global_store_dwordx2 v[22:23], v[36:37], off offset:-1536
	global_load_dwordx4 v[36:39], v[10:11], off offset:2048
	v_pk_mul_f32 v[42:43], v[46:47], v[60:61] op_sel_hi:[1,0]
	s_waitcnt vmcnt(0)
	v_pk_mul_f32 v[36:37], v[36:37], v[40:41]
	v_pk_mul_f32 v[38:39], v[38:39], v[42:43]
	v_cvt_pk_bf16_f32 v36, v36, v37
	v_cvt_pk_bf16_f32 v37, v38, v39
	global_store_dwordx2 v[22:23], v[36:37], off offset:-1024
	global_load_dwordx4 v[36:39], v[10:11], off offset:3072
	v_pk_mul_f32 v[40:41], v[48:49], v[60:61] op_sel_hi:[1,0]
	v_pk_mul_f32 v[42:43], v[50:51], v[60:61] op_sel_hi:[1,0]
	s_waitcnt vmcnt(0)
	v_pk_mul_f32 v[36:37], v[36:37], v[40:41]
	v_pk_mul_f32 v[38:39], v[38:39], v[42:43]
	v_cvt_pk_bf16_f32 v36, v36, v37
	v_cvt_pk_bf16_f32 v37, v38, v39
	global_store_dwordx2 v[22:23], v[36:37], off offset:-512
	global_load_dwordx4 v[36:39], v[12:13], off
	s_waitcnt vmcnt(0)
	v_pk_mul_f32 v[8:9], v[38:39], v[8:9]
	v_pk_mul_f32 v[6:7], v[36:37], v[6:7]
	s_nop 0
	v_cvt_pk_bf16_f32 v6, v6, v7
	v_cvt_pk_bf16_f32 v7, v8, v9
	global_store_dwordx2 v[22:23], v[6:7], off
	global_load_dwordx4 v[6:9], v[14:15], off
	s_waitcnt vmcnt(0)
	v_pk_mul_f32 v[8:9], v[34:35], v[8:9]
	v_pk_mul_f32 v[6:7], v[32:33], v[6:7]
	v_pk_mul_f32 v[32:33], v[52:53], v[60:61] op_sel_hi:[1,0]
	v_cvt_pk_bf16_f32 v6, v6, v7
	v_cvt_pk_bf16_f32 v7, v8, v9
	global_store_dwordx2 v[22:23], v[6:7], off offset:512
	global_load_dwordx4 v[6:9], v[16:17], off
	v_pk_mul_f32 v[34:35], v[54:55], v[60:61] op_sel_hi:[1,0]
	s_waitcnt vmcnt(0)
	v_pk_mul_f32 v[6:7], v[32:33], v[6:7]
	v_pk_mul_f32 v[8:9], v[34:35], v[8:9]
	v_cvt_pk_bf16_f32 v6, v6, v7
	v_cvt_pk_bf16_f32 v7, v8, v9
	global_store_dwordx2 v[22:23], v[6:7], off offset:1024
	global_load_dwordx4 v[6:9], v[18:19], off
	s_waitcnt vmcnt(0)
	v_pk_mul_f32 v[4:5], v[4:5], v[8:9]
	v_pk_mul_f32 v[2:3], v[2:3], v[6:7]
	s_nop 0
	v_cvt_pk_bf16_f32 v2, v2, v3
	v_cvt_pk_bf16_f32 v3, v4, v5
	global_store_dwordx2 v[22:23], v[2:3], off offset:1536
	v_lshl_add_u64 v[22:23], v[22:23], 0, s[6:7]
	s_cbranch_scc0 .LBB0_29
